# F K-loop: SGPR-base LDS-DMA loads (drop 16 64-bit VALU address adds per iteration), kstep bases in spare SGPR pairs
# speedup vs baseline: 1.0058x; 1.0058x over previous
; #define PG8_STAGE(bufoff, gbase, voff) do { _Pragma("unroll") for (int _i = 0; _i < 2; ++_i) \
;         __builtin_amdgcn_global_load_lds((const unsigned*)((const char*)(gbase) + (voff)[_i]), (LAS unsigned*)(lds + (bufoff) + ldsw + _i * 8192), 16, 0, 0); } while (0)
; #define PG8_LDA(dst, b, h) do { _Pragma("unroll") for (int m = 0; m < 4; ++m) _Pragma("unroll") for (int k = 0; k < 2; ++k) dst[m][k] = *(const LAS bf16x8*)(lds + PG8_SA(b, h) + aoff + m * 2048 + k * 1024); } while (0)
; #define PG8_LDB(dst, b, h) do { _Pragma("unroll") for (int n = 0; n < 2; ++n) _Pragma("unroll") for (int k = 0; k < 2; ++k) dst[n][k] = *(const LAS bf16x8*)(lds + PG8_SB(b, h) + boff + n * 2048 + k * 1024); } while (0)
; #define PG8_MMA(ai, bj, At, Bt) do { __builtin_amdgcn_s_setprio(1); _Pragma("unroll") for (int m = 0; m < 4; ++m) _Pragma("unroll") for (int n = 0; n < 2; ++n) _Pragma("unroll") for (int k = 0; k < 2; ++k) \
;         acc[ai][bj][m][n] = __builtin_amdgcn_mfma_f32_16x16x32_bf16(Bt[n][k], At[m][k], acc[ai][bj][m][n], 0, 0, 0); __builtin_amdgcn_s_setprio(0); } while (0)
; template <class Epi>
; __device__ __forceinline__ void gemm_phase(LAS unsigned char* lds, const Gemm g, const StaticOrder& S, const Epi& E) {
;     ...
;             const bool last = (t == nt - 2);
;             const char* a1 = cA + (size_t)(t + 1) * kstep;
;             const char* a2 = last ? nA : cA + (size_t)(t + 2) * kstep; const char* b2 = last ? nB : cB + (size_t)(t + 2) * kstep;
;             const char* a3 = a2 + kstep; const char* b3 = b2 + kstep;
;             PG8_LDB(B0, 0, 0); PG8_SCHED; PG8_LDA(At, 0, 0); PG8_STAGE(PG8_SA(1, 1), a1 + hstep, voffA);
;             PG8_WAIT_L(8); PG8_BAR; PG8_WAIT_L(0); PG8_MMA(0, 0, At, B0); PG8_BAR; PG8_SCHED;
;             PG8_LDB(B1, 0, 1); PG8_STAGE(PG8_SB(0, 0), b2, voffB);
;             PG8_BAR; PG8_WAIT_L(0); PG8_MMA(0, 1, At, B1); PG8_BAR;
;             PG8_LDA(At, 0, 1); PG8_STAGE(PG8_SA(0, 0), a2, voffA);
;             PG8_BAR; PG8_WAIT_L(0); PG8_MMA(1, 0, At, B0); PG8_BAR; PG8_SCHED;
;             PG8_STAGE(PG8_SB(0, 1), b2 + hstep, voffB);
;             PG8_WAIT_V(6); PG8_BAR; PG8_MMA(1, 1, At, B1); PG8_BAR;
;             PG8_LDB(B0, 1, 0); PG8_SCHED; PG8_LDA(At, 1, 0); PG8_STAGE(PG8_SA(0, 1), a2 + hstep, voffA);
;             PG8_WAIT_L(8); PG8_BAR; PG8_WAIT_L(0); PG8_MMA(0, 0, At, B0); PG8_BAR; PG8_SCHED;
.LBB0_103:
	s_add_u32 s5, s46, 0xfff00080
	s_addc_u32 s6, s47, -1
	s_add_i32 s58, 0, 0x10000
	v_add_u32_e32 v152, s58, v157
	ds_read_b128 v[130:133], v152
	ds_read_b128 v[134:137], v152 offset:1024
	ds_read_b128 v[148:151], v152 offset:2048
	ds_read_b128 v[152:155], v152 offset:3072
	s_cmp_eq_u32 s4, 60
	s_cselect_b32 s49, s25, s6
	s_cselect_b32 s48, s71, s5
	s_cselect_b32 s7, s13, vcc_hi
	s_cselect_b32 s6, s87, vcc_lo
	s_add_i32 m0, s92, 0xc000
	ds_read_b128 v[170:173], v168
	ds_read_b128 v[174:177], v168 offset:1024
	ds_read_b128 v[178:181], v168 offset:2048
	ds_read_b128 v[182:185], v168 offset:3072
	ds_read_b128 v[204:207], v168 offset:4096
	ds_read_b128 v[208:211], v168 offset:5120
	ds_read_b128 v[212:215], v168 offset:6144
	ds_read_b128 v[216:219], v168 offset:7168
	global_load_lds_dwordx4 v144, s[46:47]
	s_add_i32 m0, s92, 0xe000
	s_nop 0
	global_load_lds_dwordx4 v146, s[46:47]
	s_waitcnt lgkmcnt(8)
	s_barrier
	s_waitcnt lgkmcnt(0)
	s_setprio 1
	s_waitcnt lgkmcnt(0)
	v_mfma_f32_16x16x32_bf16 v[126:129], v[130:133], v[170:173], v[126:129]
	v_mfma_f32_16x16x32_bf16 v[122:125], v[148:151], v[170:173], v[122:125]
	v_mfma_f32_16x16x32_bf16 v[110:113], v[130:133], v[178:181], v[110:113]
	v_mfma_f32_16x16x32_bf16 v[106:109], v[148:151], v[178:181], v[106:109]
	v_mfma_f32_16x16x32_bf16 v[94:97], v[130:133], v[204:207], v[94:97]
	v_mfma_f32_16x16x32_bf16 v[90:93], v[148:151], v[204:207], v[90:93]
	v_mfma_f32_16x16x32_bf16 v[78:81], v[130:133], v[212:215], v[78:81]
	v_mfma_f32_16x16x32_bf16 v[74:77], v[148:151], v[212:215], v[74:77]
	v_mfma_f32_16x16x32_bf16 v[126:129], v[134:137], v[174:177], v[126:129]
	v_mfma_f32_16x16x32_bf16 v[122:125], v[152:155], v[174:177], v[122:125]
	v_mfma_f32_16x16x32_bf16 v[110:113], v[134:137], v[182:185], v[110:113]
	v_mfma_f32_16x16x32_bf16 v[106:109], v[152:155], v[182:185], v[106:109]
	v_mfma_f32_16x16x32_bf16 v[94:97], v[134:137], v[208:211], v[94:97]
	v_mfma_f32_16x16x32_bf16 v[90:93], v[152:155], v[208:211], v[90:93]
	v_mfma_f32_16x16x32_bf16 v[78:81], v[134:137], v[216:219], v[78:81]
	v_mfma_f32_16x16x32_bf16 v[74:77], v[152:155], v[216:219], v[74:77]
	s_setprio 0
	s_barrier
	s_add_i32 s5, 0, 0x14000
	v_add_u32_e32 v162, s5, v157
	s_add_i32 s58, s58, s91
	ds_read_b128 v[226:229], v162
	ds_read_b128 v[230:233], v162 offset:1024
	ds_read_b128 v[234:237], v162 offset:2048
	ds_read_b128 v[238:241], v162 offset:3072
	s_add_u32 s100, s6, s26
	s_addc_u32 s101, s7, s27
	s_mov_b32 m0, s58
	s_nop 0
	global_load_lds_dwordx4 v0, s[6:7]
	s_add_i32 m0, s58, 0x2000
	s_nop 0
	global_load_lds_dwordx4 v138, s[6:7]
	s_barrier
	s_waitcnt lgkmcnt(0)
	s_setprio 1
	s_waitcnt lgkmcnt(0)
	v_mfma_f32_16x16x32_bf16 v[118:121], v[226:229], v[170:173], v[118:121]
	v_mfma_f32_16x16x32_bf16 v[114:117], v[234:237], v[170:173], v[114:117]
	v_mfma_f32_16x16x32_bf16 v[102:105], v[226:229], v[178:181], v[102:105]
	v_mfma_f32_16x16x32_bf16 v[98:101], v[234:237], v[178:181], v[98:101]
	v_mfma_f32_16x16x32_bf16 v[86:89], v[226:229], v[204:207], v[86:89]
	v_mfma_f32_16x16x32_bf16 v[82:85], v[234:237], v[204:207], v[82:85]
	v_mfma_f32_16x16x32_bf16 v[70:73], v[226:229], v[212:215], v[70:73]
	v_mfma_f32_16x16x32_bf16 v[66:69], v[234:237], v[212:215], v[66:69]
	v_mfma_f32_16x16x32_bf16 v[118:121], v[230:233], v[174:177], v[118:121]
	v_mfma_f32_16x16x32_bf16 v[114:117], v[238:241], v[174:177], v[114:117]
	v_mfma_f32_16x16x32_bf16 v[102:105], v[230:233], v[182:185], v[102:105]
	v_mfma_f32_16x16x32_bf16 v[98:101], v[238:241], v[182:185], v[98:101]
	v_mfma_f32_16x16x32_bf16 v[86:89], v[230:233], v[208:211], v[86:89]
	v_mfma_f32_16x16x32_bf16 v[82:85], v[238:241], v[208:211], v[82:85]
	v_mfma_f32_16x16x32_bf16 v[70:73], v[230:233], v[216:219], v[70:73]
	v_mfma_f32_16x16x32_bf16 v[66:69], v[238:241], v[216:219], v[66:69]
	s_setprio 0
	s_mov_b32 m0, s92
	s_add_u32 s98, s48, s26
	s_addc_u32 s99, s49, s27
	s_barrier
	ds_read_b128 v[170:173], v168 offset:16384
	ds_read_b128 v[174:177], v168 offset:17408
	ds_read_b128 v[178:181], v168 offset:18432
	ds_read_b128 v[182:185], v168 offset:19456
	ds_read_b128 v[204:207], v168 offset:20480
	ds_read_b128 v[208:211], v168 offset:21504
	ds_read_b128 v[212:215], v168 offset:22528
	ds_read_b128 v[216:219], v168 offset:23552
	global_load_lds_dwordx4 v142, s[48:49]
	s_mov_b32 m0, s93
	s_nop 0
	global_load_lds_dwordx4 v140, s[48:49]
	s_barrier
	s_waitcnt lgkmcnt(0)
	s_setprio 1
	s_waitcnt lgkmcnt(0)
	v_mfma_f32_16x16x32_bf16 v[62:65], v[130:133], v[170:173], v[62:65]
	v_mfma_f32_16x16x32_bf16 v[58:61], v[148:151], v[170:173], v[58:61]
	v_mfma_f32_16x16x32_bf16 v[46:49], v[130:133], v[178:181], v[46:49]
	v_mfma_f32_16x16x32_bf16 v[42:45], v[148:151], v[178:181], v[42:45]
	v_mfma_f32_16x16x32_bf16 v[30:33], v[130:133], v[204:207], v[30:33]
	v_mfma_f32_16x16x32_bf16 v[26:29], v[148:151], v[204:207], v[26:29]
	v_mfma_f32_16x16x32_bf16 v[14:17], v[130:133], v[212:215], v[14:17]
	v_mfma_f32_16x16x32_bf16 v[10:13], v[148:151], v[212:215], v[10:13]
	v_mfma_f32_16x16x32_bf16 v[62:65], v[134:137], v[174:177], v[62:65]
	v_mfma_f32_16x16x32_bf16 v[58:61], v[152:155], v[174:177], v[58:61]
	v_mfma_f32_16x16x32_bf16 v[46:49], v[134:137], v[182:185], v[46:49]
	v_mfma_f32_16x16x32_bf16 v[42:45], v[152:155], v[182:185], v[42:45]
	v_mfma_f32_16x16x32_bf16 v[30:33], v[134:137], v[208:211], v[30:33]
	v_mfma_f32_16x16x32_bf16 v[26:29], v[152:155], v[208:211], v[26:29]
	v_mfma_f32_16x16x32_bf16 v[14:17], v[134:137], v[216:219], v[14:17]
	v_mfma_f32_16x16x32_bf16 v[10:13], v[152:155], v[216:219], v[10:13]
	s_setprio 0
	s_barrier
; #define PG8_STAGE(bufoff, gbase, voff) do { _Pragma("unroll") for (int _i = 0; _i < 2; ++_i) \
;         __builtin_amdgcn_global_load_lds((const unsigned*)((const char*)(gbase) + (voff)[_i]), (LAS unsigned*)(lds + (bufoff) + ldsw + _i * 8192), 16, 0, 0); } while (0)
; #define PG8_LDA(dst, b, h) do { _Pragma("unroll") for (int m = 0; m < 4; ++m) _Pragma("unroll") for (int k = 0; k < 2; ++k) dst[m][k] = *(const LAS bf16x8*)(lds + PG8_SA(b, h) + aoff + m * 2048 + k * 1024); } while (0)
; #define PG8_LDB(dst, b, h) do { _Pragma("unroll") for (int n = 0; n < 2; ++n) _Pragma("unroll") for (int k = 0; k < 2; ++k) dst[n][k] = *(const LAS bf16x8*)(lds + PG8_SB(b, h) + boff + n * 2048 + k * 1024); } while (0)
; #define PG8_MMA(ai, bj, At, Bt) do { __builtin_amdgcn_s_setprio(1); _Pragma("unroll") for (int m = 0; m < 4; ++m) _Pragma("unroll") for (int n = 0; n < 2; ++n) _Pragma("unroll") for (int k = 0; k < 2; ++k) \
;         acc[ai][bj][m][n] = __builtin_amdgcn_mfma_f32_16x16x32_bf16(Bt[n][k], At[m][k], acc[ai][bj][m][n], 0, 0, 0); __builtin_amdgcn_s_setprio(0); } while (0)
; #define PG8_WAIT_V(n) asm volatile("s_waitcnt vmcnt(" #n ")" ::: "memory")
; #define PG8_WAIT_L(n) asm volatile("s_waitcnt lgkmcnt(" #n ")" ::: "memory")
; #define PG8_BAR __builtin_amdgcn_s_barrier()
; #define PG8_SCHED __builtin_amdgcn_sched_barrier(0)
; template <class Epi>
; __device__ __forceinline__ void gemm_phase(LAS unsigned char* lds, const Gemm g, const StaticOrder& S, const Epi& E) {
;     ...
;             PG8_STAGE(PG8_SB(0, 1), b2 + hstep, voffB);
;             PG8_WAIT_V(6); PG8_BAR; PG8_MMA(1, 1, At, B1); PG8_BAR;
;             PG8_LDB(B0, 1, 0); PG8_SCHED; PG8_LDA(At, 1, 0); PG8_STAGE(PG8_SA(0, 1), a2 + hstep, voffA);
;             PG8_WAIT_L(8); PG8_BAR; PG8_WAIT_L(0); PG8_MMA(0, 0, At, B0); PG8_BAR; PG8_SCHED;
;             PG8_LDB(B1, 1, 1); PG8_STAGE(PG8_SB(1, 0), b3, voffB);
;             PG8_BAR; PG8_WAIT_L(0); PG8_MMA(0, 1, At, B1); PG8_BAR;
;             PG8_LDA(At, 1, 1); PG8_STAGE(PG8_SA(1, 0), a3, voffA);
;             PG8_BAR; PG8_WAIT_L(0); PG8_MMA(1, 0, At, B0); PG8_BAR; PG8_SCHED;
	s_add_u32 s60, s6, 0x100000
	s_addc_u32 s61, s7, 0
	s_add_i32 s5, s5, s91
	s_mov_b32 m0, s5
	s_nop 0
	global_load_lds_dwordx4 v0, s[60:61]
	s_add_i32 m0, s5, 0x2000
	s_nop 0
	global_load_lds_dwordx4 v138, s[60:61]
	s_waitcnt vmcnt(6)
	s_barrier
	s_setprio 1
	v_mfma_f32_16x16x32_bf16 v[54:57], v[226:229], v[170:173], v[54:57]
	v_mfma_f32_16x16x32_bf16 v[50:53], v[234:237], v[170:173], v[50:53]
	v_mfma_f32_16x16x32_bf16 v[38:41], v[226:229], v[178:181], v[38:41]
	v_mfma_f32_16x16x32_bf16 v[34:37], v[234:237], v[178:181], v[34:37]
	v_mfma_f32_16x16x32_bf16 v[22:25], v[226:229], v[204:207], v[22:25]
	v_mfma_f32_16x16x32_bf16 v[18:21], v[234:237], v[204:207], v[18:21]
	v_mfma_f32_16x16x32_bf16 v[6:9], v[226:229], v[212:215], v[6:9]
	v_mfma_f32_16x16x32_bf16 v[2:5], v[234:237], v[212:215], v[2:5]
	v_mfma_f32_16x16x32_bf16 v[54:57], v[230:233], v[174:177], v[54:57]
	v_mfma_f32_16x16x32_bf16 v[50:53], v[238:241], v[174:177], v[50:53]
	v_mfma_f32_16x16x32_bf16 v[38:41], v[230:233], v[182:185], v[38:41]
	v_mfma_f32_16x16x32_bf16 v[34:37], v[238:241], v[182:185], v[34:37]
	v_mfma_f32_16x16x32_bf16 v[22:25], v[230:233], v[208:211], v[22:25]
	v_mfma_f32_16x16x32_bf16 v[18:21], v[238:241], v[208:211], v[18:21]
	v_mfma_f32_16x16x32_bf16 v[6:9], v[230:233], v[216:219], v[6:9]
	v_mfma_f32_16x16x32_bf16 v[2:5], v[238:241], v[216:219], v[2:5]
	s_setprio 0
	s_add_i32 s5, 0, 0x18000
	v_add_u32_e32 v152, s5, v157
	s_barrier
	ds_read_b128 v[130:133], v152
	ds_read_b128 v[134:137], v152 offset:1024
	ds_read_b128 v[148:151], v152 offset:2048
	ds_read_b128 v[152:155], v152 offset:3072
	s_add_u32 s48, s48, 0x100000
	s_addc_u32 s49, s49, 0
	s_mov_b32 m0, s96
	ds_read_b128 v[170:173], v168 offset:32768
	ds_read_b128 v[174:177], v168 offset:33792
	ds_read_b128 v[178:181], v168 offset:34816
	ds_read_b128 v[182:185], v168 offset:35840
	ds_read_b128 v[204:207], v168 offset:36864
	ds_read_b128 v[208:211], v168 offset:37888
	ds_read_b128 v[212:215], v168 offset:38912
	ds_read_b128 v[216:219], v168 offset:39936
	global_load_lds_dwordx4 v142, s[48:49]
	s_mov_b32 m0, s97
	s_nop 0
	global_load_lds_dwordx4 v140, s[48:49]
	s_waitcnt lgkmcnt(8)
	s_barrier
	s_waitcnt lgkmcnt(0)
	s_setprio 1
	s_waitcnt lgkmcnt(0)
	v_mfma_f32_16x16x32_bf16 v[126:129], v[130:133], v[170:173], v[126:129]
	v_mfma_f32_16x16x32_bf16 v[122:125], v[148:151], v[170:173], v[122:125]
	v_mfma_f32_16x16x32_bf16 v[110:113], v[130:133], v[178:181], v[110:113]
	v_mfma_f32_16x16x32_bf16 v[106:109], v[148:151], v[178:181], v[106:109]
	v_mfma_f32_16x16x32_bf16 v[94:97], v[130:133], v[204:207], v[94:97]
	v_mfma_f32_16x16x32_bf16 v[90:93], v[148:151], v[204:207], v[90:93]
	v_mfma_f32_16x16x32_bf16 v[78:81], v[130:133], v[212:215], v[78:81]
	v_mfma_f32_16x16x32_bf16 v[74:77], v[148:151], v[212:215], v[74:77]
	v_mfma_f32_16x16x32_bf16 v[126:129], v[134:137], v[174:177], v[126:129]
	v_mfma_f32_16x16x32_bf16 v[122:125], v[152:155], v[174:177], v[122:125]
	v_mfma_f32_16x16x32_bf16 v[110:113], v[134:137], v[182:185], v[110:113]
	v_mfma_f32_16x16x32_bf16 v[106:109], v[152:155], v[182:185], v[106:109]
	v_mfma_f32_16x16x32_bf16 v[94:97], v[134:137], v[208:211], v[94:97]
	v_mfma_f32_16x16x32_bf16 v[90:93], v[152:155], v[208:211], v[90:93]
	v_mfma_f32_16x16x32_bf16 v[78:81], v[134:137], v[216:219], v[78:81]
	v_mfma_f32_16x16x32_bf16 v[74:77], v[152:155], v[216:219], v[74:77]
	s_setprio 0
	s_barrier
	s_add_i32 s48, 0, 0x1c000
	s_add_i32 s5, s5, s91
	v_add_u32_e32 v169, s48, v157
	s_mov_b32 m0, s5
	ds_read_b128 v[226:229], v169
	ds_read_b128 v[230:233], v169 offset:1024
	ds_read_b128 v[234:237], v169 offset:2048
	ds_read_b128 v[238:241], v169 offset:3072
	global_load_lds_dwordx4 v0, s[100:101]
	s_add_i32 m0, s5, 0x2000
	s_nop 0
	global_load_lds_dwordx4 v138, s[100:101]
	s_barrier
	s_waitcnt lgkmcnt(0)
	s_setprio 1
	s_waitcnt lgkmcnt(0)
	v_mfma_f32_16x16x32_bf16 v[118:121], v[226:229], v[170:173], v[118:121]
	v_mfma_f32_16x16x32_bf16 v[114:117], v[234:237], v[170:173], v[114:117]
	v_mfma_f32_16x16x32_bf16 v[102:105], v[226:229], v[178:181], v[102:105]
	v_mfma_f32_16x16x32_bf16 v[98:101], v[234:237], v[178:181], v[98:101]
	v_mfma_f32_16x16x32_bf16 v[86:89], v[226:229], v[204:207], v[86:89]
	v_mfma_f32_16x16x32_bf16 v[82:85], v[234:237], v[204:207], v[82:85]
	v_mfma_f32_16x16x32_bf16 v[70:73], v[226:229], v[212:215], v[70:73]
	v_mfma_f32_16x16x32_bf16 v[66:69], v[234:237], v[212:215], v[66:69]
	v_mfma_f32_16x16x32_bf16 v[118:121], v[230:233], v[174:177], v[118:121]
	v_mfma_f32_16x16x32_bf16 v[114:117], v[238:241], v[174:177], v[114:117]
	v_mfma_f32_16x16x32_bf16 v[102:105], v[230:233], v[182:185], v[102:105]
	v_mfma_f32_16x16x32_bf16 v[98:101], v[238:241], v[182:185], v[98:101]
	v_mfma_f32_16x16x32_bf16 v[86:89], v[230:233], v[208:211], v[86:89]
	v_mfma_f32_16x16x32_bf16 v[82:85], v[238:241], v[208:211], v[82:85]
	v_mfma_f32_16x16x32_bf16 v[70:73], v[230:233], v[216:219], v[70:73]
	v_mfma_f32_16x16x32_bf16 v[66:69], v[238:241], v[216:219], v[66:69]
	s_setprio 0
	s_mov_b32 m0, s54
	s_barrier
	ds_read_b128 v[170:173], v168 offset:49152
	ds_read_b128 v[174:177], v168 offset:50176
	ds_read_b128 v[178:181], v168 offset:51200
	ds_read_b128 v[182:185], v168 offset:52224
	ds_read_b128 v[204:207], v168 offset:53248
	ds_read_b128 v[208:211], v168 offset:54272
	ds_read_b128 v[212:215], v168 offset:55296
	ds_read_b128 v[216:219], v168 offset:56320
	global_load_lds_dwordx4 v142, s[98:99]
	s_mov_b32 m0, s84
	s_nop 0
	global_load_lds_dwordx4 v140, s[98:99]
	s_barrier
; #define PG8_STAGE(bufoff, gbase, voff) do { _Pragma("unroll") for (int _i = 0; _i < 2; ++_i) \
;         __builtin_amdgcn_global_load_lds((const unsigned*)((const char*)(gbase) + (voff)[_i]), (LAS unsigned*)(lds + (bufoff) + ldsw + _i * 8192), 16, 0, 0); } while (0)
; #define PG8_MMA(ai, bj, At, Bt) do { __builtin_amdgcn_s_setprio(1); _Pragma("unroll") for (int m = 0; m < 4; ++m) _Pragma("unroll") for (int n = 0; n < 2; ++n) _Pragma("unroll") for (int k = 0; k < 2; ++k) \
;         acc[ai][bj][m][n] = __builtin_amdgcn_mfma_f32_16x16x32_bf16(Bt[n][k], At[m][k], acc[ai][bj][m][n], 0, 0, 0); __builtin_amdgcn_s_setprio(0); } while (0)
; #define PG8_WAIT_V(n) asm volatile("s_waitcnt vmcnt(" #n ")" ::: "memory")
; #define PG8_WAIT_L(n) asm volatile("s_waitcnt lgkmcnt(" #n ")" ::: "memory")
; #define PG8_BAR __builtin_amdgcn_s_barrier()
; #define PG8_SCHED __builtin_amdgcn_sched_barrier(0)
; template <class Epi>
; __device__ __forceinline__ void gemm_phase(LAS unsigned char* lds, const Gemm g, const StaticOrder& S, const Epi& E) {
;     ...
;             PG8_BAR; PG8_WAIT_L(0); PG8_MMA(1, 0, At, B0); PG8_BAR; PG8_SCHED;
;             PG8_STAGE(PG8_SB(1, 1), b3 + hstep, voffB);
;             PG8_WAIT_V(6); PG8_BAR; PG8_MMA(1, 1, At, B1); PG8_BAR;
;         }
	s_waitcnt lgkmcnt(0)
	s_setprio 1
	s_waitcnt lgkmcnt(0)
	v_mfma_f32_16x16x32_bf16 v[62:65], v[130:133], v[170:173], v[62:65]
	v_mfma_f32_16x16x32_bf16 v[58:61], v[148:151], v[170:173], v[58:61]
	v_mfma_f32_16x16x32_bf16 v[46:49], v[130:133], v[178:181], v[46:49]
	v_mfma_f32_16x16x32_bf16 v[42:45], v[148:151], v[178:181], v[42:45]
	v_mfma_f32_16x16x32_bf16 v[30:33], v[130:133], v[204:207], v[30:33]
	v_mfma_f32_16x16x32_bf16 v[26:29], v[148:151], v[204:207], v[26:29]
	v_mfma_f32_16x16x32_bf16 v[14:17], v[130:133], v[212:215], v[14:17]
	v_mfma_f32_16x16x32_bf16 v[10:13], v[148:151], v[212:215], v[10:13]
	v_mfma_f32_16x16x32_bf16 v[62:65], v[134:137], v[174:177], v[62:65]
	v_mfma_f32_16x16x32_bf16 v[58:61], v[152:155], v[174:177], v[58:61]
	v_mfma_f32_16x16x32_bf16 v[46:49], v[134:137], v[182:185], v[46:49]
	v_mfma_f32_16x16x32_bf16 v[42:45], v[152:155], v[182:185], v[42:45]
	v_mfma_f32_16x16x32_bf16 v[30:33], v[134:137], v[208:211], v[30:33]
	v_mfma_f32_16x16x32_bf16 v[26:29], v[152:155], v[208:211], v[26:29]
	v_mfma_f32_16x16x32_bf16 v[14:17], v[134:137], v[216:219], v[14:17]
	v_mfma_f32_16x16x32_bf16 v[10:13], v[152:155], v[216:219], v[10:13]
	s_setprio 0
	s_barrier
	s_add_u32 s6, s6, 0x100080
	s_addc_u32 s7, s7, 0
	s_add_i32 s5, s48, s91
	s_mov_b32 m0, s5
	s_nop 0
	global_load_lds_dwordx4 v0, s[6:7]
	s_add_i32 m0, s5, 0x2000
	s_nop 0
	global_load_lds_dwordx4 v138, s[6:7]
	s_waitcnt vmcnt(6)
	s_barrier
	s_setprio 1
	v_mfma_f32_16x16x32_bf16 v[54:57], v[226:229], v[170:173], v[54:57]
	v_mfma_f32_16x16x32_bf16 v[50:53], v[234:237], v[170:173], v[50:53]
	v_mfma_f32_16x16x32_bf16 v[38:41], v[226:229], v[178:181], v[38:41]
	v_mfma_f32_16x16x32_bf16 v[34:37], v[234:237], v[178:181], v[34:37]
	v_mfma_f32_16x16x32_bf16 v[22:25], v[226:229], v[204:207], v[22:25]
	v_mfma_f32_16x16x32_bf16 v[18:21], v[234:237], v[204:207], v[18:21]
	v_mfma_f32_16x16x32_bf16 v[6:9], v[226:229], v[212:215], v[6:9]
	v_mfma_f32_16x16x32_bf16 v[2:5], v[234:237], v[212:215], v[2:5]
	v_mfma_f32_16x16x32_bf16 v[54:57], v[230:233], v[174:177], v[54:57]
	v_mfma_f32_16x16x32_bf16 v[50:53], v[238:241], v[174:177], v[50:53]
	v_mfma_f32_16x16x32_bf16 v[38:41], v[230:233], v[182:185], v[38:41]
	v_mfma_f32_16x16x32_bf16 v[34:37], v[238:241], v[182:185], v[34:37]
	v_mfma_f32_16x16x32_bf16 v[22:25], v[230:233], v[208:211], v[22:25]
	v_mfma_f32_16x16x32_bf16 v[18:21], v[238:241], v[208:211], v[18:21]
	v_mfma_f32_16x16x32_bf16 v[6:9], v[230:233], v[216:219], v[6:9]
	v_mfma_f32_16x16x32_bf16 v[2:5], v[238:241], v[216:219], v[2:5]
	s_setprio 0
	s_add_i32 s4, s4, 2
	s_add_u32 s46, s46, 0x100
	s_addc_u32 s47, s47, 0
	s_add_u32 vcc_lo, vcc_lo, 0x100
	s_addc_u32 vcc_hi, vcc_hi, 0
	s_cmp_gt_u32 s4, 61
	s_barrier
	s_cbranch_scc0 .LBB0_103
; __device__ __forceinline__ unsigned pk2(float lo, float hi) { unsigned r; asm("v_cvt_pk_bf16_f32 %0, %1, %2" : "=v"(r) : "v"(lo), "v"(hi)); return r; }
; __device__ __forceinline__ float bf_lo(unsigned w) { return __uint_as_float(w << 16); }
; __device__ __forceinline__ float bf_hi(unsigned w) { return __uint_as_float(w & 0xffff0000u); }
;     __device__ __forceinline__ void operator()(const f32x4 (&acc)[2][2][4][2], const Unit& u, int  , int wr, int wc, int fr, int fq) const {
;         const int row0 = u.pm * BM + wr * 64 + fr, col0 = u.pn * BM + wc * 32 + 8 * fq;
;         u32x4 rv[2][2];
; #pragma unroll
;         for (int bj = 0; bj < 2; ++bj) rv[0][bj] = *(const u32x4*)(hb + (size_t)row0 * DM + col0 + bj * HALF);
; #pragma unroll
;         for (int g = 0; g < 8; ++g) {
;             const int ai = g >> 2, m = g & 3;
;             const int row = row0 + ai * HALF + m * 16; const size_t off = (size_t)row * DM + col0; float s = 0.f;
;             if (g < 7) { const int g1 = g + 1; const size_t off1 = (size_t)(row0 + (g1 >> 2) * HALF + (g1 & 3) * 16) * DM + col0;
; #pragma unroll
;                 for (int bj = 0; bj < 2; ++bj) rv[g1 & 1][bj] = *(const u32x4*)(hb + off1 + bj * HALF); }
; #pragma unroll
;             for (int bj = 0; bj < 2; ++bj) {
;                 const u32x4 r = rv[g & 1][bj]; const f32x4 a0 = acc[ai][bj][m][0], a1 = acc[ai][bj][m][1];
;                 u32x4 o; o.x = pk2(bf_lo(r.x) + a0[0], bf_hi(r.x) + a0[1]); o.y = pk2(bf_lo(r.y) + a0[2], bf_hi(r.y) + a0[3]);
;                 o.z = pk2(bf_lo(r.z) + a1[0], bf_hi(r.z) + a1[1]); o.w = pk2(bf_lo(r.w) + a1[2], bf_hi(r.w) + a1[3]);
;                 *(u32x4*)(hb + off + bj * HALF) = o;
; #pragma unroll
;                 for (int e = 0; e < 4; ++e) { const float x0 = bf_lo(o[e]), x1 = bf_hi(o[e]); s += x0 * x0 + x1 * x1; }
;             }
;             s += __shfl_xor(s, 16); s += __shfl_xor(s, 32);
;             if (fq == 0) ssq[(size_t)row * 16 + u.pn * 4 + wc] = s;
	v_lshl_add_u32 v150, s86, 8, v156
	v_lshl_or_b32 v148, s18, 8, v166
	v_ashrrev_i32_e32 v151, 31, v150
	v_lshlrev_b64 v[130:131], 11, v[150:151]
	v_ashrrev_i32_e32 v149, 31, v148
	v_lshl_add_u64 v[130:131], s[8:9], 0, v[130:131]
	v_lshlrev_b64 v[132:133], 1, v[148:149]
	v_lshl_add_u64 v[162:163], v[130:131], 0, v[132:133]
	global_load_dwordx4 v[170:173], v[162:163], off
	global_load_dwordx4 v[174:177], v[162:163], off offset:256
	v_or_b32_e32 v152, 16, v150
	v_ashrrev_i32_e32 v153, 31, v152
	v_lshlrev_b64 v[130:131], 11, v[152:153]
	v_lshl_add_u64 v[130:131], s[8:9], 0, v[130:131]
	v_lshl_add_u64 v[154:155], v[130:131], 0, v[132:133]
	global_load_dwordx4 v[134:137], v[154:155], off
	global_load_dwordx4 v[130:133], v[154:155], off offset:256
	v_lshlrev_b32_e32 v202, 11, v150
	v_lshl_add_u32 v202, v148, 1, v202
	v_add_u32_e32 v202, 0x10000, v202
	global_load_dwordx4 v[204:207], v202, s[8:9]
	global_load_dwordx4 v[208:211], v202, s[8:9] offset:256
	v_add_u32_e32 v202, 0x8000, v202
	global_load_dwordx4 v[212:215], v202, s[8:9]
	global_load_dwordx4 v[216:219], v202, s[8:9] offset:256
	v_add_u32_e32 v202, 0x28000, v202
	global_load_dwordx4 v[226:229], v202, s[8:9]
	global_load_dwordx4 v[230:233], v202, s[8:9] offset:256
	v_add_u32_e32 v202, 0x8000, v202
	global_load_dwordx4 v[234:237], v202, s[8:9]
	global_load_dwordx4 v[238:241], v202, s[8:9] offset:256
	v_add_u32_e32 v202, 0x8000, v202
	global_load_dwordx4 v[158:161], v202, s[8:9]
	global_load_dwordx4 v[188:191], v202, s[8:9] offset:256
	v_add_u32_e32 v202, 0x8000, v202
	global_load_dwordx4 v[194:197], v202, s[8:9]
	global_load_dwordx4 v[198:201], v202, s[8:9] offset:256
	v_and_b32_e32 v178, 64, v193
	v_xor_b32_e32 v169, 16, v193
	s_lshl_b32 s6, s18, 2
	s_ashr_i32 s7, s6, 31
	s_waitcnt vmcnt(12)
	v_lshlrev_b32_e32 v181, 16, v172
	v_lshlrev_b32_e32 v182, 16, v173
	v_and_b32_e32 v173, 0xffff0000, v173
	v_lshlrev_b32_e32 v185, 16, v176
	v_and_b32_e32 v176, 0xffff0000, v176
	v_lshlrev_b32_e32 v179, 16, v170
	v_and_b32_e32 v170, 0xffff0000, v170
	v_lshlrev_b32_e32 v180, 16, v171
	v_and_b32_e32 v171, 0xffff0000, v171
	v_and_b32_e32 v172, 0xffff0000, v172
	v_lshlrev_b32_e32 v183, 16, v174
	v_and_b32_e32 v174, 0xffff0000, v174
	v_lshlrev_b32_e32 v186, 16, v177
	v_and_b32_e32 v177, 0xffff0000, v177
	v_add_f32_e32 v122, v122, v181
	v_add_f32_e32 v125, v125, v173
	v_add_f32_e32 v115, v115, v176
	v_add_f32_e32 v126, v126, v179
	v_add_f32_e32 v127, v127, v170
	v_add_f32_e32 v128, v128, v180
	v_add_f32_e32 v129, v129, v171
	v_add_f32_e32 v123, v123, v172
	v_add_f32_e32 v124, v124, v182
	v_add_f32_e32 v170, v118, v183
	v_add_f32_e32 v171, v119, v174
	v_add_f32_e32 v114, v114, v185
	v_add_f32_e32 v173, v116, v186
	v_add_f32_e32 v174, v117, v177
	v_cvt_pk_bf16_f32 v116, v126, v127
	v_cvt_pk_bf16_f32 v117, v128, v129
	v_cvt_pk_bf16_f32 v118, v122, v123
	v_cvt_pk_bf16_f32 v119, v124, v125
	v_cvt_pk_bf16_f32 v122, v114, v115
	v_lshlrev_b32_e32 v184, 16, v175
	v_and_b32_e32 v115, 0xffff0000, v116
	v_and_b32_e32 v125, 0xffff0000, v117
	v_lshlrev_b32_e32 v114, 16, v116
	v_lshlrev_b32_e32 v124, 16, v117
	v_and_b32_e32 v127, 0xffff0000, v118
	v_mul_f32_e32 v115, v115, v115
	v_mul_f32_e32 v125, v125, v125
	v_and_b32_e32 v175, 0xffff0000, v175
	v_lshlrev_b32_e32 v126, 16, v118
	v_and_b32_e32 v129, 0xffff0000, v119
	v_mul_f32_e32 v127, v127, v127
	v_fmac_f32_e32 v115, v114, v114
	v_fmac_f32_e32 v125, v124, v124
	v_add_f32_e32 v172, v120, v184
	v_add_f32_e32 v121, v121, v175
	v_cvt_pk_bf16_f32 v120, v170, v171
	v_lshlrev_b32_e32 v128, 16, v119
	v_and_b32_e32 v171, 0xffff0000, v120
	v_mul_f32_e32 v129, v129, v129
	v_fmac_f32_e32 v127, v126, v126
	v_add_f32_e32 v114, v115, v125
	v_cvt_pk_bf16_f32 v121, v172, v121
	v_cvt_pk_bf16_f32 v123, v173, v174
	v_lshlrev_b32_e32 v170, 16, v120
	v_and_b32_e32 v173, 0xffff0000, v121
	v_mul_f32_e32 v171, v171, v171
	v_fmac_f32_e32 v129, v128, v128
	v_add_f32_e32 v114, v114, v127
	v_lshlrev_b32_e32 v172, 16, v121
	v_and_b32_e32 v175, 0xffff0000, v122
	v_mul_f32_e32 v173, v173, v173
	v_fmac_f32_e32 v171, v170, v170
	v_add_f32_e32 v114, v114, v129
	v_lshlrev_b32_e32 v174, 16, v122
	v_and_b32_e32 v177, 0xffff0000, v123
	v_mul_f32_e32 v175, v175, v175
	v_fmac_f32_e32 v173, v172, v172
	v_add_f32_e32 v114, v114, v171
	v_add_u32_e32 v115, 64, v178
	v_lshlrev_b32_e32 v176, 16, v123
	v_mul_f32_e32 v177, v177, v177
	v_fmac_f32_e32 v175, v174, v174
	v_add_f32_e32 v114, v114, v173
	v_cmp_lt_i32_e32 vcc, v169, v115
	v_fmac_f32_e32 v177, v176, v176
	v_add_f32_e32 v114, v114, v175
	v_cndmask_b32_e32 v124, v193, v169, vcc
	v_add_f32_e32 v114, v114, v177
	v_lshlrev_b32_e32 v126, 2, v124
	ds_bpermute_b32 v124, v126, v114
	global_store_dwordx4 v[162:163], v[116:119], off
	global_store_dwordx4 v[162:163], v[120:123], off offset:256
	s_waitcnt lgkmcnt(0)
	v_add_f32_e32 v114, v114, v124
	v_xor_b32_e32 v124, 32, v193
	v_cmp_lt_i32_e32 vcc, v124, v115
	s_nop 1
	v_cndmask_b32_e32 v115, v193, v124, vcc
	v_lshlrev_b32_e32 v127, 2, v115
	ds_bpermute_b32 v115, v127, v114
	s_and_saveexec_b64 s[46:47], s[40:41]
	s_cbranch_execz .LBB0_106
	s_waitcnt lgkmcnt(0)
	v_add_f32_e32 v116, v114, v115
	v_lshlrev_b64 v[114:115], 6, v[150:151]
	v_lshl_add_u64 v[114:115], s[10:11], 0, v[114:115]
	v_lshl_add_u64 v[114:115], s[6:7], 2, v[114:115]
	s_lshl_b32 s18, s83, 2
	v_lshl_add_u64 v[114:115], v[114:115], 0, s[18:19]
	global_store_dword v[114:115], v116, off
